# attention loop: K/V LDS staging addresses hoisted out of the tile loop (two lane bases + immediate offsets instead of eight 64-bit mads per tile)
# baseline (speedup 1.0000x reference)
.LBB0_390:
	s_or_b64 exec, exec, s[8:9]
	v_add_u32_e32 v10, v5, v142
	v_ashrrev_i32_e32 v11, 31, v10
	v_and_b32_e32 v1, 7, v1
	v_lshlrev_b64 v[122:123], 10, v[10:11]
	v_lshl_add_u64 v[10:11], s[16:17], 0, v[122:123]
	v_lshlrev_b32_e32 v112, 7, v1
	v_lshl_add_u64 v[10:11], v[10:11], 0, v[112:113]
	v_mov_b32_e32 v119, v113
	v_lshl_add_u64 v[10:11], v[10:11], 0, v[118:119]
	v_ashrrev_i32_e32 v7, 31, v6
	global_load_dwordx4 v[64:67], v[10:11], off
	global_load_dwordx4 v[68:71], v[10:11], off offset:32
	global_load_dwordx4 v[72:75], v[10:11], off offset:64
	global_load_dwordx4 v[76:79], v[10:11], off offset:96
	v_lshlrev_b64 v[10:11], 19, v[6:7]
	v_lshl_or_b32 v6, v6, 3, v1
	v_lshl_add_u64 v[10:11], s[20:21], 0, v[10:11]
	v_ashrrev_i32_e32 v7, 31, v6
	v_ashrrev_i32_e32 v5, 31, v4
	v_lshl_add_u64 v[124:125], v[10:11], 0, v[112:113]
	v_lshlrev_b64 v[10:11], 16, v[6:7]
	v_lshlrev_b64 v[4:5], 10, v[4:5]
	v_lshl_add_u64 v[126:127], s[26:27], 0, v[10:11]
	v_lshl_add_u64 v[10:11], s[18:19], 0, v[4:5]
	v_mov_b32_e32 v3, v131
	v_lshl_add_u64 v[10:11], v[10:11], 0, v[112:113]
	v_lshlrev_b64 v[12:13], 15, v[6:7]
	v_lshl_add_u64 v[128:129], s[30:31], 0, v[12:13]
	v_lshlrev_b32_e32 v16, 4, v3
	v_cndmask_b32_e32 v11, v125, v11, vcc
	v_cndmask_b32_e32 v10, v124, v10, vcc
	v_and_b32_e32 v14, 0x70, v16
	v_mov_b32_e32 v15, v113
	v_cndmask_b32_e32 v13, v127, v129, vcc
	v_cndmask_b32_e32 v12, v126, v128, vcc
	v_lshl_add_u64 v[10:11], v[10:11], 0, v[14:15]
	v_and_b32_e32 v14, 48, v16
	v_lshl_add_u64 v[12:13], v[12:13], 0, v[14:15]
	v_ashrrev_i32_e32 v14, 3, v3
	v_ashrrev_i32_e32 v15, 31, v14
	v_lshlrev_b64 v[14:15], 10, v[14:15]
	v_lshl_add_u64 v[14:15], v[10:11], 0, v[14:15]
	global_load_dwordx4 v[80:83], v[14:15], off
	v_ashrrev_i32_e32 v14, 2, v3
	v_ashrrev_i32_e32 v15, 31, v14
	v_lshlrev_b64 v[14:15], v2, v[14:15]
	v_lshl_add_u64 v[14:15], v[14:15], 1, v[12:13]
	v_add_u32_e32 v16, 64, v3
	global_load_dwordx4 v[84:87], v[14:15], off
	v_ashrrev_i32_e32 v14, 3, v16
	v_ashrrev_i32_e32 v15, 31, v14
	v_lshlrev_b64 v[14:15], 10, v[14:15]
	v_lshl_add_u64 v[14:15], v[10:11], 0, v[14:15]
	global_load_dwordx4 v[88:91], v[14:15], off
	v_ashrrev_i32_e32 v14, 2, v16
	v_ashrrev_i32_e32 v15, 31, v14
	v_lshlrev_b64 v[14:15], v2, v[14:15]
	v_lshl_add_u64 v[14:15], v[14:15], 1, v[12:13]
	v_add_u32_e32 v16, 0x80, v3
	global_load_dwordx4 v[92:95], v[14:15], off
	v_ashrrev_i32_e32 v14, 3, v16
	v_ashrrev_i32_e32 v15, 31, v14
	v_lshlrev_b64 v[14:15], 10, v[14:15]
	v_lshl_add_u64 v[14:15], v[10:11], 0, v[14:15]
	global_load_dwordx4 v[96:99], v[14:15], off
	v_ashrrev_i32_e32 v14, 2, v16
	v_ashrrev_i32_e32 v15, 31, v14
	v_lshlrev_b64 v[14:15], v2, v[14:15]
	v_lshl_add_u64 v[14:15], v[14:15], 1, v[12:13]
	v_add_u32_e32 v3, 0xc0, v3
	global_load_dwordx4 v[100:103], v[14:15], off
	v_ashrrev_i32_e32 v14, 3, v3
	v_ashrrev_i32_e32 v15, 31, v14
	v_lshlrev_b64 v[14:15], 10, v[14:15]
	v_lshl_add_u64 v[10:11], v[10:11], 0, v[14:15]
	global_load_dwordx4 v[104:107], v[10:11], off
	v_ashrrev_i32_e32 v10, 2, v3
	v_ashrrev_i32_e32 v11, 31, v10
	v_lshlrev_b64 v[2:3], v2, v[10:11]
	v_lshl_add_u64 v[2:3], v[2:3], 1, v[12:13]
	global_load_dwordx4 v[108:111], v[2:3], off
	v_lshlrev_b32_e32 v130, 6, v1
	v_mul_u32_u24_e32 v1, 0x1d1, v1
	v_lshlrev_b32_e32 v2, 2, v1
	v_sub_u32_e64 v1, v8, 4 clamp
	v_min_u32_e32 v119, 56, v1
	v_ashrrev_i32_e32 v1, 31, v0
	v_lshlrev_b64 v[0:1], 10, v[0:1]
	v_lshl_add_u64 v[0:1], s[18:19], 0, v[0:1]
	v_lshl_add_u64 v[134:135], v[0:1], 0, v[112:113]
	v_lshlrev_b64 v[0:1], 19, v[6:7]
	v_or_b32_e32 v151, v9, v142
	v_lshl_add_u64 v[136:137], s[28:29], 0, v[0:1]
	v_sub_u32_e64 v0, v151, 8 clamp
	v_mov_b32_e32 v3, v113
	v_min_u32_e32 v153, 48, v0
	v_or_b32_e32 v4, v4, v112
	v_mov_b32_e32 v155, 0
	v_lshl_add_u64 v[132:133], s[14:15], 0, v[2:3]
	v_sub_u32_e32 v152, v119, v8
	v_add_u32_e32 v154, 16, v153
	v_lshl_add_u64 v[138:139], s[34:35], 0, v[4:5]
	v_mov_b32_e32 v156, 0xff800000
	s_mov_b32 s65, 0
	s_mov_b32 s63, 32
	s_mov_b64 s[40:41], 0
	s_xor_b64 s[42:43], vcc, -1
	v_mov_b32_e32 v0, 0
	v_mov_b32_e32 v1, v155
	v_mov_b32_e32 v2, v155
	v_mov_b32_e32 v3, v155
	v_mov_b32_e32 v4, v155
	v_mov_b32_e32 v5, v155
	v_mov_b32_e32 v6, v155
	v_mov_b32_e32 v7, v155
	v_mov_b32_e32 v8, v155
	v_mov_b32_e32 v9, v155
	v_mov_b32_e32 v10, v155
	v_mov_b32_e32 v11, v155
	v_mov_b32_e32 v12, v155
	v_mov_b32_e32 v13, v155
	v_mov_b32_e32 v14, v155
	v_mov_b32_e32 v15, v155
	v_mov_b32_e32 v16, 0
	v_mov_b32_e32 v17, v155
	v_mov_b32_e32 v18, v155
	v_mov_b32_e32 v19, v155
	v_mov_b32_e32 v20, v155
	v_mov_b32_e32 v21, v155
	v_mov_b32_e32 v22, v155
	v_mov_b32_e32 v23, v155
	v_mov_b32_e32 v24, v155
	v_mov_b32_e32 v25, v155
	v_mov_b32_e32 v26, v155
	v_mov_b32_e32 v27, v155
	v_mov_b32_e32 v28, v155
	v_mov_b32_e32 v29, v155
	v_mov_b32_e32 v30, v155
	v_mov_b32_e32 v31, v155
	v_lshlrev_b32_e32 v222, 4, v131
	v_and_b32_e32 v220, 0x70, v222
	v_and_b32_e32 v221, 48, v222
	v_lshrrev_b32_e32 v222, 3, v131
	v_mad_u32_u24 v220, v222, s48, v220
	v_add_u32_e32 v220, v143, v220
	v_lshrrev_b32_e32 v222, 2, v131
	v_mad_u32_u24 v221, v222, s61, v221
	v_add_u32_e32 v221, v143, v221
	s_branch .LBB0_393

.LBB0_393:
	s_add_i32 s64, s65, 1
	s_waitcnt vmcnt(7)
	ds_write_b128 v220, v[80:83]
	s_waitcnt vmcnt(6)
	ds_write_b128 v221, v[84:87] offset:4608
	s_waitcnt vmcnt(5)
	ds_write_b128 v220, v[88:91] offset:1152
	s_waitcnt vmcnt(4)
	ds_write_b128 v221, v[92:95] offset:5888
	s_waitcnt vmcnt(3)
	ds_write_b128 v220, v[96:99] offset:2304
	s_waitcnt vmcnt(2)
	ds_write_b128 v221, v[100:103] offset:7168
	s_waitcnt vmcnt(1)
	ds_write_b128 v220, v[104:107] offset:3456
	v_cmp_lt_u32_e32 vcc, s64, v150
	s_waitcnt vmcnt(0)
	ds_write_b128 v221, v[108:111] offset:8448
	ds_read_b128 v[158:161], v147
	ds_read_b128 v[162:165], v147 offset:32
	ds_read_b128 v[166:169], v147 offset:64
	ds_read_b128 v[170:173], v147 offset:96
	s_and_saveexec_b64 s[8:9], vcc
	s_cbranch_execz .LBB0_401
	v_mov_b32_e32 v38, v131
	v_mov_b64_e32 v[32:33], 0x100
	v_mov_b32_e32 v112, s63
	v_mov_b64_e32 v[36:37], v[128:129]
	v_mov_b64_e32 v[34:35], v[138:139]
	s_and_saveexec_b64 s[44:45], s[6:7]
	s_cbranch_execz .LBB0_400
	s_cmp_gt_u32 s65, 14
	s_mov_b64 s[46:47], -1
	s_cbranch_scc0 .LBB0_397
	s_add_i32 s36, s65, -15
	s_lshr_b32 s36, s36, 1
	v_add_u32_e32 v36, s36, v119
	s_and_b32 s66, s63, 32
	v_lshl_or_b32 v112, v36, 6, s66
	v_lshlrev_b64 v[32:33], 10, v[112:113]
	v_lshlrev_b32_e32 v112, 7, v36
	v_lshl_add_u64 v[34:35], v[134:135], 0, v[32:33]
	v_lshl_add_u64 v[36:37], v[136:137], 0, v[112:113]
	s_mov_b64 s[46:47], 0
